# code placement: every K-loop 32-MFMA run starts at byte phase 4 mod 8 (s_nop padding ahead of the load segment's closing wait)
# baseline (speedup 1.0000x reference)
; #define PG8_STAGE(bufoff, gbase, voff) do { _Pragma("unroll") for (int _i = 0; _i < 2; ++_i) \
;         __builtin_amdgcn_global_load_lds((const unsigned*)((const char*)(gbase) + (voff)[_i]), (LAS unsigned*)(lds + (bufoff) + ldsw + _i * 8192), 16, 0, 0); } while (0)
; #define PG8_LDA(dst, b, h) do { _Pragma("unroll") for (int m = 0; m < 4; ++m) _Pragma("unroll") for (int k = 0; k < 2; ++k) dst[m][k] = *(const LAS bf16x8*)(lds + PG8_SA(b, h) + aoff + m * 2048 + k * 1024); } while (0)
; #define PG8_LDB(dst, b, h) do { _Pragma("unroll") for (int n = 0; n < 2; ++n) _Pragma("unroll") for (int k = 0; k < 2; ++k) dst[n][k] = *(const LAS bf16x8*)(lds + PG8_SB(b, h) + boff + n * 2048 + k * 1024); } while (0)
; #define PG8_MMA(ai, bj, At, Bt) do { __builtin_amdgcn_s_setprio(1); _Pragma("unroll") for (int m = 0; m < 4; ++m) _Pragma("unroll") for (int n = 0; n < 2; ++n) _Pragma("unroll") for (int k = 0; k < 2; ++k) \
;         acc[ai][bj][m][n] = __builtin_amdgcn_mfma_f32_16x16x32_bf16(Bt[n][k], At[m][k], acc[ai][bj][m][n], 0, 0, 0); __builtin_amdgcn_s_setprio(0); } while (0)
; #define PG8_WAIT_V(n) asm volatile("s_waitcnt vmcnt(" #n ")" ::: "memory")
; #define PG8_WAIT_L(n) asm volatile("s_waitcnt lgkmcnt(" #n ")" ::: "memory")
; #define PG8_BAR __builtin_amdgcn_s_barrier()
; template <class Epi>
; __device__ __forceinline__ void gemm_phase(LAS unsigned char* lds, const Gemm g, const StaticOrder& S, const Epi& E, const int tid) {
;     ...
;             const char* a2 = last ? nA : (s2 ? cA2 + (size_t)(t + 2 - nt) * kstep : cA + (size_t)(t + 2) * kstep);
;             const char* b2 = last ? nB : (s2 ? cB2 + (size_t)(t + 2 - nt) * kstep : cB + (size_t)(t + 2) * kstep);
;             const char* a3 = a2 + kstep; const char* b3 = b2 + kstep;
;             if constexpr (Epi::TWO) { if (t == nt) E.mid(acc, cur, wr, wc, fr, fq); }
;             if constexpr (SP2) {
;             PG8_LDB(B0, 0, 0); PG8_LDB(B1, 0, 1); PG8_SCHED; PG8_LDA(At, 0, 0); PG8_STAGE(PG8_SA(1, 1), a1 + hstep, voffA);
;             PG8_WAIT_V(8); PG8_WAIT_L(0); PG8_BAR; PG8_MMA(0, 0, At, B0); PG8_MMA(0, 1, At, B1); PG8_BAR; PG8_SCHED;
;             PG8_LDA(At, 0, 1); PG8_STAGE(PG8_SB(0, 0), b2, voffB); PG8_STAGE(PG8_SB(0, 1), b2 + bhs, voffB); PG8_STAGE(PG8_SA(0, 0), a2, voffA);
;             PG8_WAIT_V(8); PG8_WAIT_L(0); PG8_BAR; PG8_MMA(1, 0, At, B0); PG8_MMA(1, 1, At, B1); PG8_BAR; PG8_SCHED;
.LBB0_126:
	s_add_u32 s30, s28, 0xffe00080
	s_addc_u32 s31, s29, -1
	s_add_i32 s52, 0, 0x10000
	s_cmpk_eq_i32 s51, 0x7c
	s_cselect_b32 s35, s17, s31
	s_cselect_b32 s34, s27, s30
	s_cselect_b32 s31, s15, s50
	s_cselect_b32 s30, s33, s49
	s_add_i32 s54, 0, 0x14000
	v_add_u32_e32 v30, s52, v193
	v_add_u32_e32 v54, s54, v193
	ds_read_b128 v[18:21], v30
	ds_read_b128 v[22:25], v30 offset:1024
	ds_read_b128 v[26:29], v30 offset:2048
	ds_read_b128 v[30:33], v30 offset:3072
	ds_read_b128 v[42:45], v54
	ds_read_b128 v[46:49], v54 offset:1024
	ds_read_b128 v[50:53], v54 offset:2048
	ds_read_b128 v[54:57], v54 offset:3072
	v_lshl_add_u64 v[172:173], s[28:29], 0, v[180:181]
	s_add_i32 m0, s37, 0xc000
	ds_read_b128 v[182:185], v199
	global_load_lds_dwordx4 v[172:173], off
	ds_read_b128 v[186:189], v199 offset:1024
	ds_read_b128 v[212:215], v199 offset:2048
	v_lshl_add_u64 v[172:173], s[28:29], 0, v[178:179]
	s_add_i32 m0, s37, 0xe000
	s_nop 0
	global_load_lds_dwordx4 v[172:173], off
	ds_read_b128 v[216:219], v199 offset:3072
	ds_read_b128 v[220:223], v199 offset:4096
	ds_read_b128 v[224:227], v199 offset:5120
	ds_read_b128 v[228:231], v199 offset:6144
	ds_read_b128 v[232:235], v199 offset:7168
	s_waitcnt vmcnt(8)
	s_waitcnt lgkmcnt(0)
	s_barrier
	s_setprio 1
	s_waitcnt lgkmcnt(0)
	v_mfma_f32_16x16x32_bf16 v[158:161], v[18:21], v[182:185], v[158:161]
	v_mfma_f32_16x16x32_bf16 v[154:157], v[26:29], v[182:185], v[154:157]
	v_mfma_f32_16x16x32_bf16 v[142:145], v[18:21], v[212:215], v[142:145]
	v_mfma_f32_16x16x32_bf16 v[138:141], v[26:29], v[212:215], v[138:141]
	v_mfma_f32_16x16x32_bf16 v[126:129], v[18:21], v[220:223], v[126:129]
	v_mfma_f32_16x16x32_bf16 v[122:125], v[26:29], v[220:223], v[122:125]
	v_mfma_f32_16x16x32_bf16 v[110:113], v[18:21], v[228:231], v[110:113]
	v_mfma_f32_16x16x32_bf16 v[106:109], v[26:29], v[228:231], v[106:109]
	v_mfma_f32_16x16x32_bf16 v[158:161], v[22:25], v[186:189], v[158:161]
	v_mfma_f32_16x16x32_bf16 v[154:157], v[30:33], v[186:189], v[154:157]
	v_mfma_f32_16x16x32_bf16 v[142:145], v[22:25], v[216:219], v[142:145]
	v_mfma_f32_16x16x32_bf16 v[138:141], v[30:33], v[216:219], v[138:141]
	v_mfma_f32_16x16x32_bf16 v[126:129], v[22:25], v[224:227], v[126:129]
	v_mfma_f32_16x16x32_bf16 v[122:125], v[30:33], v[224:227], v[122:125]
	v_mfma_f32_16x16x32_bf16 v[110:113], v[22:25], v[232:235], v[110:113]
	v_mfma_f32_16x16x32_bf16 v[106:109], v[30:33], v[232:235], v[106:109]
	s_setprio 0
	s_setprio 1
	v_mfma_f32_16x16x32_bf16 v[150:153], v[42:45], v[182:185], v[150:153]
	v_mfma_f32_16x16x32_bf16 v[146:149], v[50:53], v[182:185], v[146:149]
	v_mfma_f32_16x16x32_bf16 v[134:137], v[42:45], v[212:215], v[134:137]
	v_mfma_f32_16x16x32_bf16 v[130:133], v[50:53], v[212:215], v[130:133]
	v_mfma_f32_16x16x32_bf16 v[118:121], v[42:45], v[220:223], v[118:121]
	v_mfma_f32_16x16x32_bf16 v[114:117], v[50:53], v[220:223], v[114:117]
	v_mfma_f32_16x16x32_bf16 v[102:105], v[42:45], v[228:231], v[102:105]
	v_mfma_f32_16x16x32_bf16 v[98:101], v[50:53], v[228:231], v[98:101]
	v_mfma_f32_16x16x32_bf16 v[150:153], v[46:49], v[186:189], v[150:153]
	v_mfma_f32_16x16x32_bf16 v[146:149], v[54:57], v[186:189], v[146:149]
	v_mfma_f32_16x16x32_bf16 v[134:137], v[46:49], v[216:219], v[134:137]
	v_mfma_f32_16x16x32_bf16 v[130:133], v[54:57], v[216:219], v[130:133]
	v_mfma_f32_16x16x32_bf16 v[118:121], v[46:49], v[224:227], v[118:121]
	v_mfma_f32_16x16x32_bf16 v[114:117], v[54:57], v[224:227], v[114:117]
	v_mfma_f32_16x16x32_bf16 v[102:105], v[46:49], v[232:235], v[102:105]
	v_mfma_f32_16x16x32_bf16 v[98:101], v[54:57], v[232:235], v[98:101]
	s_setprio 0
	s_barrier
	s_add_i32 s52, s52, s36
	v_lshl_add_u64 v[172:173], s[30:31], 0, v[0:1]
	s_mov_b32 m0, s52
	ds_read_b128 v[182:185], v199 offset:16384
	global_load_lds_dwordx4 v[172:173], off
	ds_read_b128 v[186:189], v199 offset:17408
	ds_read_b128 v[212:215], v199 offset:18432
	s_add_i32 m0, s52, 0x2000
	s_add_u32 s52, s30, 0x20000
	v_lshl_add_u64 v[174:175], s[30:31], 0, v[166:167]
	s_addc_u32 s53, s31, 0
	s_add_i32 s54, s54, s36
	global_load_lds_dwordx4 v[174:175], off
	ds_read_b128 v[216:219], v199 offset:19456
	ds_read_b128 v[220:223], v199 offset:20480
	v_lshl_add_u64 v[176:177], s[52:53], 0, v[0:1]
	s_mov_b32 m0, s54
	v_lshl_add_u64 v[200:201], s[34:35], 0, v[164:165]
	global_load_lds_dwordx4 v[176:177], off
	ds_read_b128 v[224:227], v199 offset:21504
	ds_read_b128 v[228:231], v199 offset:22528
	v_lshl_add_u64 v[176:177], s[52:53], 0, v[166:167]
	s_add_i32 m0, s54, 0x2000
	s_nop 0
	global_load_lds_dwordx4 v[176:177], off
	ds_read_b128 v[232:235], v199 offset:23552
	v_lshl_add_u64 v[176:177], s[34:35], 0, v[162:163]
	s_mov_b32 m0, s37
	s_nop 0
	global_load_lds_dwordx4 v[176:177], off
	s_mov_b32 m0, s38
	s_nop 0
	global_load_lds_dwordx4 v[200:201], off
	s_nop 0
	s_waitcnt vmcnt(8)
	s_waitcnt lgkmcnt(0)
	s_barrier
; #define PG8_STAGE(bufoff, gbase, voff) do { _Pragma("unroll") for (int _i = 0; _i < 2; ++_i) \
;         __builtin_amdgcn_global_load_lds((const unsigned*)((const char*)(gbase) + (voff)[_i]), (LAS unsigned*)(lds + (bufoff) + ldsw + _i * 8192), 16, 0, 0); } while (0)
; #define PG8_LDA(dst, b, h) do { _Pragma("unroll") for (int m = 0; m < 4; ++m) _Pragma("unroll") for (int k = 0; k < 2; ++k) dst[m][k] = *(const LAS bf16x8*)(lds + PG8_SA(b, h) + aoff + m * 2048 + k * 1024); } while (0)
; #define PG8_LDB(dst, b, h) do { _Pragma("unroll") for (int n = 0; n < 2; ++n) _Pragma("unroll") for (int k = 0; k < 2; ++k) dst[n][k] = *(const LAS bf16x8*)(lds + PG8_SB(b, h) + boff + n * 2048 + k * 1024); } while (0)
; #define PG8_MMA(ai, bj, At, Bt) do { __builtin_amdgcn_s_setprio(1); _Pragma("unroll") for (int m = 0; m < 4; ++m) _Pragma("unroll") for (int n = 0; n < 2; ++n) _Pragma("unroll") for (int k = 0; k < 2; ++k) \
;         acc[ai][bj][m][n] = __builtin_amdgcn_mfma_f32_16x16x32_bf16(Bt[n][k], At[m][k], acc[ai][bj][m][n], 0, 0, 0); __builtin_amdgcn_s_setprio(0); } while (0)
; #define PG8_WAIT_V(n) asm volatile("s_waitcnt vmcnt(" #n ")" ::: "memory")
; #define PG8_WAIT_L(n) asm volatile("s_waitcnt lgkmcnt(" #n ")" ::: "memory")
; #define PG8_BAR __builtin_amdgcn_s_barrier()
; #define PG8_SCHED __builtin_amdgcn_sched_barrier(0)
; template <class Epi>
; __device__ __forceinline__ void gemm_phase(LAS unsigned char* lds, const Gemm g, const StaticOrder& S, const Epi& E, const int tid) {
;     ...
;             PG8_WAIT_V(8); PG8_WAIT_L(0); PG8_BAR; PG8_MMA(1, 0, At, B0); PG8_MMA(1, 1, At, B1); PG8_BAR; PG8_SCHED;
;             PG8_LDB(B0, 1, 0); PG8_LDB(B1, 1, 1); PG8_SCHED; PG8_LDA(At, 1, 0); PG8_STAGE(PG8_SA(0, 1), a2 + hstep, voffA);
;             PG8_WAIT_V(8); PG8_WAIT_L(0); PG8_BAR; PG8_MMA(0, 0, At, B0); PG8_MMA(0, 1, At, B1); PG8_BAR; PG8_SCHED;
	s_setprio 1
	s_waitcnt lgkmcnt(0)
	v_mfma_f32_16x16x32_bf16 v[94:97], v[18:21], v[182:185], v[94:97]
	v_mfma_f32_16x16x32_bf16 v[90:93], v[26:29], v[182:185], v[90:93]
	v_mfma_f32_16x16x32_bf16 v[78:81], v[18:21], v[212:215], v[78:81]
	v_mfma_f32_16x16x32_bf16 v[74:77], v[26:29], v[212:215], v[74:77]
	v_mfma_f32_16x16x32_bf16 v[62:65], v[18:21], v[220:223], v[62:65]
	v_mfma_f32_16x16x32_bf16 v[58:61], v[26:29], v[220:223], v[58:61]
	v_mfma_f32_16x16x32_bf16 v[14:17], v[18:21], v[228:231], v[14:17]
	v_mfma_f32_16x16x32_bf16 v[10:13], v[26:29], v[228:231], v[10:13]
	v_mfma_f32_16x16x32_bf16 v[94:97], v[22:25], v[186:189], v[94:97]
	v_mfma_f32_16x16x32_bf16 v[90:93], v[30:33], v[186:189], v[90:93]
	v_mfma_f32_16x16x32_bf16 v[78:81], v[22:25], v[216:219], v[78:81]
	v_mfma_f32_16x16x32_bf16 v[74:77], v[30:33], v[216:219], v[74:77]
	v_mfma_f32_16x16x32_bf16 v[62:65], v[22:25], v[224:227], v[62:65]
	v_mfma_f32_16x16x32_bf16 v[58:61], v[30:33], v[224:227], v[58:61]
	v_mfma_f32_16x16x32_bf16 v[14:17], v[22:25], v[232:235], v[14:17]
	v_mfma_f32_16x16x32_bf16 v[10:13], v[30:33], v[232:235], v[10:13]
	s_setprio 0
	s_setprio 1
	v_mfma_f32_16x16x32_bf16 v[38:41], v[42:45], v[220:223], v[38:41]
	v_mfma_f32_16x16x32_bf16 v[34:37], v[50:53], v[220:223], v[34:37]
	v_mfma_f32_16x16x32_bf16 v[6:9], v[42:45], v[228:231], v[6:9]
	v_mfma_f32_16x16x32_bf16 v[2:5], v[50:53], v[228:231], v[2:5]
	v_mfma_f32_16x16x32_bf16 v[18:21], v[42:45], v[182:185], v[86:89]
	v_mfma_f32_16x16x32_bf16 v[22:25], v[50:53], v[182:185], v[82:85]
	v_mfma_f32_16x16x32_bf16 v[26:29], v[42:45], v[212:215], v[70:73]
	v_mfma_f32_16x16x32_bf16 v[30:33], v[50:53], v[212:215], v[66:69]
	v_mfma_f32_16x16x32_bf16 v[38:41], v[46:49], v[224:227], v[38:41]
	v_mfma_f32_16x16x32_bf16 v[34:37], v[54:57], v[224:227], v[34:37]
	v_mfma_f32_16x16x32_bf16 v[6:9], v[46:49], v[232:235], v[6:9]
	v_mfma_f32_16x16x32_bf16 v[2:5], v[54:57], v[232:235], v[2:5]
	v_mfma_f32_16x16x32_bf16 v[18:21], v[46:49], v[186:189], v[18:21]
	v_mfma_f32_16x16x32_bf16 v[22:25], v[54:57], v[186:189], v[22:25]
	v_mfma_f32_16x16x32_bf16 v[26:29], v[46:49], v[216:219], v[26:29]
	v_mfma_f32_16x16x32_bf16 v[30:33], v[54:57], v[216:219], v[30:33]
	s_setprio 0
	s_barrier
	s_add_i32 s52, 0, 0x18000
	s_add_i32 s53, 0, 0x1c000
	v_add_u32_e32 v54, s52, v193
	v_add_u32_e32 v66, s53, v193
	ds_read_b128 v[42:45], v54
	ds_read_b128 v[46:49], v54 offset:1024
	ds_read_b128 v[50:53], v54 offset:2048
	ds_read_b128 v[54:57], v54 offset:3072
	ds_read_b128 v[182:185], v66
	ds_read_b128 v[186:189], v66 offset:1024
	ds_read_b128 v[212:215], v66 offset:2048
	ds_read_b128 v[216:219], v66 offset:3072
	s_add_u32 s34, s34, 0x200000
	s_addc_u32 s35, s35, 0
	s_mov_b32 m0, s39
	v_lshl_add_u64 v[236:237], s[34:35], 0, v[162:163]
	ds_read_b128 v[66:69], v199 offset:32768
	global_load_lds_dwordx4 v[236:237], off
	ds_read_b128 v[70:73], v199 offset:33792
	ds_read_b128 v[82:85], v199 offset:34816
	v_lshl_add_u64 v[236:237], s[34:35], 0, v[164:165]
	s_mov_b32 m0, s44
	s_nop 0
	global_load_lds_dwordx4 v[236:237], off
	ds_read_b128 v[86:89], v199 offset:35840
	ds_read_b128 v[220:223], v199 offset:36864
	ds_read_b128 v[224:227], v199 offset:37888
	ds_read_b128 v[228:231], v199 offset:38912
	ds_read_b128 v[232:235], v199 offset:39936
	s_nop 0
	s_waitcnt vmcnt(8)
	s_waitcnt lgkmcnt(0)
	s_barrier
	s_setprio 1
	s_waitcnt lgkmcnt(0)
	v_mfma_f32_16x16x32_bf16 v[158:161], v[42:45], v[66:69], v[158:161]
	v_mfma_f32_16x16x32_bf16 v[154:157], v[50:53], v[66:69], v[154:157]
	v_mfma_f32_16x16x32_bf16 v[142:145], v[42:45], v[82:85], v[142:145]
	v_mfma_f32_16x16x32_bf16 v[138:141], v[50:53], v[82:85], v[138:141]
	v_mfma_f32_16x16x32_bf16 v[126:129], v[42:45], v[220:223], v[126:129]
	v_mfma_f32_16x16x32_bf16 v[122:125], v[50:53], v[220:223], v[122:125]
	v_mfma_f32_16x16x32_bf16 v[110:113], v[42:45], v[228:231], v[110:113]
	v_mfma_f32_16x16x32_bf16 v[106:109], v[50:53], v[228:231], v[106:109]
	v_mfma_f32_16x16x32_bf16 v[158:161], v[46:49], v[70:73], v[158:161]
	v_mfma_f32_16x16x32_bf16 v[154:157], v[54:57], v[70:73], v[154:157]
	v_mfma_f32_16x16x32_bf16 v[142:145], v[46:49], v[86:89], v[142:145]
	v_mfma_f32_16x16x32_bf16 v[138:141], v[54:57], v[86:89], v[138:141]
	v_mfma_f32_16x16x32_bf16 v[126:129], v[46:49], v[224:227], v[126:129]
	v_mfma_f32_16x16x32_bf16 v[122:125], v[54:57], v[224:227], v[122:125]
	v_mfma_f32_16x16x32_bf16 v[110:113], v[46:49], v[232:235], v[110:113]
	v_mfma_f32_16x16x32_bf16 v[106:109], v[54:57], v[232:235], v[106:109]
	s_setprio 0
	s_setprio 1
	v_mfma_f32_16x16x32_bf16 v[150:153], v[182:185], v[66:69], v[150:153]
	v_mfma_f32_16x16x32_bf16 v[66:69], v[212:215], v[66:69], v[146:149]
	v_mfma_f32_16x16x32_bf16 v[146:149], v[216:219], v[70:73], v[66:69]
	v_mfma_f32_16x16x32_bf16 v[66:69], v[182:185], v[82:85], v[134:137]
	v_mfma_f32_16x16x32_bf16 v[134:137], v[186:189], v[86:89], v[66:69]
	v_mfma_f32_16x16x32_bf16 v[66:69], v[212:215], v[82:85], v[130:133]
	v_mfma_f32_16x16x32_bf16 v[130:133], v[216:219], v[86:89], v[66:69]
	v_mfma_f32_16x16x32_bf16 v[66:69], v[182:185], v[220:223], v[118:121]
	v_mfma_f32_16x16x32_bf16 v[118:121], v[186:189], v[224:227], v[66:69]
	v_mfma_f32_16x16x32_bf16 v[66:69], v[212:215], v[220:223], v[114:117]
	v_mfma_f32_16x16x32_bf16 v[114:117], v[216:219], v[224:227], v[66:69]
	v_mfma_f32_16x16x32_bf16 v[66:69], v[182:185], v[228:231], v[102:105]
	v_mfma_f32_16x16x32_bf16 v[102:105], v[186:189], v[232:235], v[66:69]
	v_mfma_f32_16x16x32_bf16 v[66:69], v[212:215], v[228:231], v[98:101]
	v_mfma_f32_16x16x32_bf16 v[150:153], v[186:189], v[70:73], v[150:153]
	v_mfma_f32_16x16x32_bf16 v[98:101], v[216:219], v[232:235], v[66:69]
	s_setprio 0
	s_barrier
; #define PG8_STAGE(bufoff, gbase, voff) do { _Pragma("unroll") for (int _i = 0; _i < 2; ++_i) \
;         __builtin_amdgcn_global_load_lds((const unsigned*)((const char*)(gbase) + (voff)[_i]), (LAS unsigned*)(lds + (bufoff) + ldsw + _i * 8192), 16, 0, 0); } while (0)
; #define PG8_LDA(dst, b, h) do { _Pragma("unroll") for (int m = 0; m < 4; ++m) _Pragma("unroll") for (int k = 0; k < 2; ++k) dst[m][k] = *(const LAS bf16x8*)(lds + PG8_SA(b, h) + aoff + m * 2048 + k * 1024); } while (0)
; #define PG8_MMA(ai, bj, At, Bt) do { __builtin_amdgcn_s_setprio(1); _Pragma("unroll") for (int m = 0; m < 4; ++m) _Pragma("unroll") for (int n = 0; n < 2; ++n) _Pragma("unroll") for (int k = 0; k < 2; ++k) \
;         acc[ai][bj][m][n] = __builtin_amdgcn_mfma_f32_16x16x32_bf16(Bt[n][k], At[m][k], acc[ai][bj][m][n], 0, 0, 0); __builtin_amdgcn_s_setprio(0); } while (0)
; #define PG8_WAIT_V(n) asm volatile("s_waitcnt vmcnt(" #n ")" ::: "memory")
; #define PG8_WAIT_L(n) asm volatile("s_waitcnt lgkmcnt(" #n ")" ::: "memory")
; #define PG8_BAR __builtin_amdgcn_s_barrier()
; #define PG8_SCHED __builtin_amdgcn_sched_barrier(0)
; template <class Epi>
; __device__ __forceinline__ void gemm_phase(LAS unsigned char* lds, const Gemm g, const StaticOrder& S, const Epi& E, const int tid) {
;     ...
;             PG8_LDA(At, 1, 1); PG8_STAGE(PG8_SB(1, 0), b3, voffB); PG8_STAGE(PG8_SB(1, 1), b3 + bhs, voffB); PG8_STAGE(PG8_SA(1, 0), a3, voffA);
;             PG8_WAIT_V(8); PG8_WAIT_L(0); PG8_BAR; PG8_MMA(1, 0, At, B0); PG8_MMA(1, 1, At, B1); PG8_BAR; PG8_SCHED;
;     ...
;         if (ALIGN_EPI) { if (wr == 0) PG8_BAR; }
	s_add_i32 s34, s52, s36
	v_lshl_add_u64 v[82:83], v[172:173], 0, s[70:71]
	s_mov_b32 m0, s34
	s_nop 0
	ds_read_b128 v[66:69], v199 offset:49152
	global_load_lds_dwordx4 v[82:83], off
	ds_read_b128 v[70:73], v199 offset:50176
	ds_read_b128 v[220:223], v199 offset:51200
	s_add_i32 m0, s34, 0x2000
	s_add_u32 s30, s30, 0x20080
	v_lshl_add_u64 v[82:83], v[174:175], 0, s[70:71]
	s_addc_u32 s31, s31, 0
	s_add_i32 s34, s53, s36
	global_load_lds_dwordx4 v[82:83], off
	ds_read_b128 v[224:227], v199 offset:52224
	ds_read_b128 v[228:231], v199 offset:53248
	v_lshl_add_u64 v[82:83], s[30:31], 0, v[0:1]
	s_mov_b32 m0, s34
	s_nop 0
	global_load_lds_dwordx4 v[82:83], off
	ds_read_b128 v[232:235], v199 offset:54272
	ds_read_b128 v[236:239], v199 offset:55296
	v_lshl_add_u64 v[82:83], s[30:31], 0, v[166:167]
	s_add_i32 m0, s34, 0x2000
	s_nop 0
	global_load_lds_dwordx4 v[82:83], off
	ds_read_b128 v[240:243], v199 offset:56320
	v_lshl_add_u64 v[82:83], v[176:177], 0, s[70:71]
	s_mov_b32 m0, s45
	s_nop 0
	global_load_lds_dwordx4 v[82:83], off
	v_lshl_add_u64 v[82:83], v[200:201], 0, s[70:71]
	s_mov_b32 m0, s46
	s_nop 0
	global_load_lds_dwordx4 v[82:83], off
	s_nop 0
	s_waitcnt vmcnt(8)
	s_waitcnt lgkmcnt(0)
	s_barrier
	s_setprio 1
	s_waitcnt lgkmcnt(0)
	v_mfma_f32_16x16x32_bf16 v[82:85], v[42:45], v[66:69], v[94:97]
	v_mfma_f32_16x16x32_bf16 v[94:97], v[46:49], v[70:73], v[82:85]
	v_mfma_f32_16x16x32_bf16 v[82:85], v[50:53], v[66:69], v[90:93]
	v_mfma_f32_16x16x32_bf16 v[78:81], v[42:45], v[220:223], v[78:81]
	v_mfma_f32_16x16x32_bf16 v[74:77], v[50:53], v[220:223], v[74:77]
	v_mfma_f32_16x16x32_bf16 v[62:65], v[42:45], v[228:231], v[62:65]
	v_mfma_f32_16x16x32_bf16 v[58:61], v[50:53], v[228:231], v[58:61]
	v_mfma_f32_16x16x32_bf16 v[14:17], v[42:45], v[236:239], v[14:17]
	v_mfma_f32_16x16x32_bf16 v[10:13], v[50:53], v[236:239], v[10:13]
	v_mfma_f32_16x16x32_bf16 v[90:93], v[54:57], v[70:73], v[82:85]
	v_mfma_f32_16x16x32_bf16 v[78:81], v[46:49], v[224:227], v[78:81]
	v_mfma_f32_16x16x32_bf16 v[74:77], v[54:57], v[224:227], v[74:77]
	v_mfma_f32_16x16x32_bf16 v[62:65], v[46:49], v[232:235], v[62:65]
	v_mfma_f32_16x16x32_bf16 v[58:61], v[54:57], v[232:235], v[58:61]
	v_mfma_f32_16x16x32_bf16 v[14:17], v[46:49], v[240:243], v[14:17]
	v_mfma_f32_16x16x32_bf16 v[10:13], v[54:57], v[240:243], v[10:13]
	s_setprio 0
	s_setprio 1
	v_mfma_f32_16x16x32_bf16 v[18:21], v[182:185], v[66:69], v[18:21]
	v_mfma_f32_16x16x32_bf16 v[86:89], v[186:189], v[70:73], v[18:21]
	v_mfma_f32_16x16x32_bf16 v[18:21], v[212:215], v[66:69], v[22:25]
	v_mfma_f32_16x16x32_bf16 v[82:85], v[216:219], v[70:73], v[18:21]
	v_mfma_f32_16x16x32_bf16 v[18:21], v[182:185], v[220:223], v[26:29]
	v_mfma_f32_16x16x32_bf16 v[70:73], v[186:189], v[224:227], v[18:21]
	v_mfma_f32_16x16x32_bf16 v[18:21], v[212:215], v[220:223], v[30:33]
	v_mfma_f32_16x16x32_bf16 v[66:69], v[216:219], v[224:227], v[18:21]
	v_mfma_f32_16x16x32_bf16 v[18:21], v[182:185], v[228:231], v[38:41]
	v_mfma_f32_16x16x32_bf16 v[38:41], v[186:189], v[232:235], v[18:21]
	v_mfma_f32_16x16x32_bf16 v[18:21], v[212:215], v[228:231], v[34:37]
	v_mfma_f32_16x16x32_bf16 v[6:9], v[182:185], v[236:239], v[6:9]
	v_mfma_f32_16x16x32_bf16 v[2:5], v[212:215], v[236:239], v[2:5]
	v_mfma_f32_16x16x32_bf16 v[34:37], v[216:219], v[232:235], v[18:21]
	v_mfma_f32_16x16x32_bf16 v[6:9], v[186:189], v[240:243], v[6:9]
	v_mfma_f32_16x16x32_bf16 v[2:5], v[216:219], v[240:243], v[2:5]
	s_setprio 0
	s_barrier
	s_add_i32 s51, s51, 2
	s_add_u32 s49, s49, 0x100
	s_addc_u32 s50, s50, 0
	s_add_u32 s28, s28, 0x100
	s_addc_u32 s29, s29, 0
	s_cmpk_gt_u32 s51, 0x7d
	s_cbranch_scc0 .LBB0_126
	s_and_b64 vcc, exec, s[12:13]
	s_cbranch_vccz .LBB0_129
	s_barrier
